# v3 + de-phase waves 4-7 (s_sleep 16) before the attention query-subtile loop
# baseline (speedup 1.0000x reference)
; #define LBAR() do { asm volatile("s_waitcnt lgkmcnt(0)" ::: "memory"); __builtin_amdgcn_s_barrier(); asm volatile("" ::: "memory"); } while (0)
; __device__ __forceinline__ void attn_unit(const AtArgs& A, unsigned char* lds, int unit, int tid, int wave, int lane) {
;     ...
;         for (int i = 0; i < 4; ++i) { VT[(c8 * 8 + 2 * i) * VST + pkey] = (bf16)(ww[i] & 0xffffu); VT[(c8 * 8 + 2 * i + 1) * VST + pkey] = (bf16)(ww[i] >> 16); }
;     }
;     *(u32x4*)(VT + (tid >> 3) * VST + (32 + (tid & 7)) * 8) = (u32x4){0u, 0u, 0u, 0u};
;     LBAR();
;     const int g = wave >> 1, qh = wave & 1, hq = kvh * 4 + g;
;     const float sink = A.sinks[hq];
; #pragma unroll 1
.LBB0_509:
	s_or_b64 exec, exec, s[16:17]
	s_waitcnt vmcnt(0)
	ds_write_b16 v72, v0 offset:36864
	ds_write_b16_d16_hi v73, v0 offset:37552
	ds_write_b16 v72, v1 offset:38240
	ds_write_b16_d16_hi v73, v1 offset:38928
	ds_write_b16 v72, v2 offset:39616
	ds_write_b16_d16_hi v73, v2 offset:40304
	ds_write_b16 v72, v3 offset:40992
	ds_write_b16_d16_hi v73, v3 offset:41680
	ds_write_b128 v74, v[104:107] offset:37376
	s_lshl_b32 s6, s10, 2
	v_readlane_b32 s44, v242, 1
	s_waitcnt lgkmcnt(0)
	s_barrier
	v_mov_b32_e32 v0, s6
	v_readlane_b32 s54, v242, 11
	v_readlane_b32 s55, v242, 12
	s_lshr_b32 s6, s24, 5
	s_and_b32 s6, s6, 1
	s_lshl_b32 s6, s6, 8
	s_and_b32 s12, s35, 31
	s_add_i32 s6, s15, s6
	global_load_dword v38, v0, s[54:55]
	s_lshl_b32 s18, s12, 17
	s_lshl_b64 s[10:11], s[6:7], 1
	s_lshl_b32 s6, s12, 7
	s_cmp_lg_u32 s3, 0
	s_cselect_b64 s[16:17], -1, 0
	s_lshl_b64 s[12:13], s[20:21], 22
	s_or_b32 s3, s12, s18
	s_add_u32 s10, s3, s10
	s_addc_u32 s11, s13, s11
	s_add_u32 s0, s6, s0
	s_addc_u32 s1, 0, s1
	v_lshl_add_u64 v[0:1], s[0:1], 0, v[48:49]
	v_lshlrev_b64 v[0:1], 6, v[0:1]
	v_lshl_add_u64 v[52:53], v[46:47], 0, s[10:11]
	v_lshl_add_u64 v[54:55], s[8:9], 0, v[0:1]
	s_mov_b32 s3, 0xb000
	s_mov_b64 s[20:21], 0
	v_mov_b32_e32 v94, v87
	v_mov_b32_e32 v95, v86
	v_readlane_b32 s45, v242, 2
	v_readlane_b32 s46, v242, 3
	v_readlane_b32 s47, v242, 4
	v_readlane_b32 s48, v242, 5
	v_readlane_b32 s49, v242, 6
	v_readlane_b32 s50, v242, 7
	v_readlane_b32 s51, v242, 8
	v_readlane_b32 s52, v242, 9
	v_readlane_b32 s53, v242, 10
	v_readlane_b32 s56, v242, 13
	v_readlane_b32 s57, v242, 14
	v_readlane_b32 s58, v242, 15
	v_readlane_b32 s59, v242, 16
	v_readlane_b32 s98, v242, 17
	s_cmp_lt_u32 s98, 4
	s_cbranch_scc1 .Lattn_nodelay
	s_sleep 16
.Lattn_nodelay:
	s_branch .LBB0_511

; __global__ void __launch_bounds__(512, 2) mega_fwd(Args a) {
	.amdhsa_kernel _Z8mega_fwd4Args
		.amdhsa_group_segment_fixed_size 0
		.amdhsa_private_segment_fixed_size 0
		.amdhsa_kernarg_size 504
		.amdhsa_user_sgpr_count 2
		.amdhsa_user_sgpr_dispatch_ptr 0
		.amdhsa_user_sgpr_queue_ptr 0
		.amdhsa_user_sgpr_kernarg_segment_ptr 1
		.amdhsa_user_sgpr_dispatch_id 0
		.amdhsa_user_sgpr_kernarg_preload_length 0
		.amdhsa_user_sgpr_kernarg_preload_offset 0
		.amdhsa_user_sgpr_private_segment_size 0
		.amdhsa_uses_dynamic_stack 0
		.amdhsa_enable_private_segment 0
		.amdhsa_system_sgpr_workgroup_id_x 1
		.amdhsa_system_sgpr_workgroup_id_y 0
		.amdhsa_system_sgpr_workgroup_id_z 0
		.amdhsa_system_sgpr_workgroup_info 0
		.amdhsa_system_vgpr_workitem_id 2
		.amdhsa_next_free_vgpr 243
		.amdhsa_next_free_sgpr 102
		.amdhsa_accum_offset 244
		.amdhsa_reserve_vcc 1
		.amdhsa_float_round_mode_32 0
		.amdhsa_float_round_mode_16_64 0
		.amdhsa_float_denorm_mode_32 3
		.amdhsa_float_denorm_mode_16_64 3
		.amdhsa_dx10_clamp 1
		.amdhsa_ieee_mode 1
		.amdhsa_fp16_overflow 0
		.amdhsa_tg_split 0
		.amdhsa_exception_fp_ieee_invalid_op 0
		.amdhsa_exception_fp_denorm_src 0
		.amdhsa_exception_fp_ieee_div_zero 0
		.amdhsa_exception_fp_ieee_overflow 0
		.amdhsa_exception_fp_ieee_underflow 0
		.amdhsa_exception_fp_ieee_inexact 0
		.amdhsa_exception_int_div_zero 0
	.end_amdhsa_kernel

; __global__ void __launch_bounds__(512, 2) mega_fwd(Args a) {
amdhsa.kernels:
  - .agpr_count:     0
    .args:
      - .offset:         0
        .size:           248
        .value_kind:     by_value
      - .offset:         248
        .size:           4
        .value_kind:     hidden_block_count_x
      - .offset:         252
        .size:           4
        .value_kind:     hidden_block_count_y
      - .offset:         256
        .size:           4
        .value_kind:     hidden_block_count_z
      - .offset:         260
        .size:           2
        .value_kind:     hidden_group_size_x
      - .offset:         262
        .size:           2
        .value_kind:     hidden_group_size_y
      - .offset:         264
        .size:           2
        .value_kind:     hidden_group_size_z
      - .offset:         266
        .size:           2
        .value_kind:     hidden_remainder_x
      - .offset:         268
        .size:           2
        .value_kind:     hidden_remainder_y
      - .offset:         270
        .size:           2
        .value_kind:     hidden_remainder_z
      - .offset:         288
        .size:           8
        .value_kind:     hidden_global_offset_x
      - .offset:         296
        .size:           8
        .value_kind:     hidden_global_offset_y
      - .offset:         304
        .size:           8
        .value_kind:     hidden_global_offset_z
      - .offset:         312
        .size:           2
        .value_kind:     hidden_grid_dims
      - .offset:         336
        .size:           8
        .value_kind:     hidden_multigrid_sync_arg
      - .offset:         368
        .size:           4
        .value_kind:     hidden_dynamic_lds_size
    .group_segment_fixed_size: 0
    .kernarg_segment_align: 8
    .kernarg_segment_size: 504
    .language:       OpenCL C
    .language_version:
      - 2
      - 0
    .max_flat_workgroup_size: 512
    .name:           _Z8mega_fwd4Args
    .private_segment_fixed_size: 0
    .sgpr_count:     108
    .sgpr_spill_count: 151
    .symbol:         _Z8mega_fwd4Args.kd
    .uniform_work_group_size: 1
    .uses_dynamic_stack: false
    .vgpr_count:     243
    .vgpr_spill_count: 0
    .wavefront_size: 64
